# post phase: butterfly all-reduce steps in registers (DPP quad_perm/half_mirror/ror, permlane16/32 swap) instead of ds_bpermute round trips
# speedup vs baseline: 1.0081x; 1.0015x over previous
; __device__ __forceinline__ void unpack8(const u32x4 w, float (&f)[8]) { f[0] = bflo(w.x); f[1] = bfhi(w.x); f[2] = bflo(w.y); f[3] = bfhi(w.y); f[4] = bflo(w.z); f[5] = bfhi(w.z); f[6] = bflo(w.w); f[7] = bfhi(w.w); }
; __device__ __forceinline__ void post_phase(const KAS Args& a, LAS unsigned char* lds, int i, const int tid_, const int bid, const int nblk) {
;     ...
;           for (int k = 0; k < 2; ++k) { const int m = mb + k * stride;
;               float y[8], vc[8], vp[8], g[8], o[8];
;               unpack8(ry[k], y); unpack8(rvc[k], vc); unpack8(rvp[k], vp); unpack8(rg[k], g);
;               float s = 0.f;
; #pragma unroll
;               for (int e = 0; e < 8; ++e) s += y[e];
;               s += __shfl_xor(s, 1); s += __shfl_xor(s, 2); s += __shfl_xor(s, 4);
;               const float mean = s * (1.0f / 64.0f); float q = 0.f;
; #pragma unroll
;               for (int e = 0; e < 8; ++e) { const float d = y[e] - mean; q += d * d; }
;               q += __shfl_xor(q, 1); q += __shfl_xor(q, 2); q += __shfl_xor(q, 4);
;               const float rstd = 1.0f / sqrtf(q * (1.0f / 64.0f) + 64e-5f);
; #pragma unroll
;               for (int e = 0; e < 8; ++e) { const float vs = vc[e] + (vp[e] - vc[e]) * muv[e]; o[e] = ((y[e] - mean) * rstd * gg[e] + gb[e] + bon[k] * vs) * g[e]; }
.LBB0_148:
	s_mul_i32 s14, s6, 0xc00
	s_mul_hi_i32 s11, s6, 0xc00
	s_add_u32 s14, s88, s14
	s_addc_u32 s15, s89, s11
	s_waitcnt vmcnt(5)
	v_lshlrev_b32_e32 v74, 16, v48
	v_lshl_add_u64 v[72:73], s[14:15], 0, v[2:3]
	v_and_b32_e32 v75, 0xffff0000, v48
	v_add_f32_e32 v2, 0, v74
	v_add_f32_e32 v2, v2, v75
	v_lshlrev_b32_e32 v76, 16, v49
	v_and_b32_e32 v77, 0xffff0000, v49
	v_add_f32_e32 v2, v2, v76
	v_add_f32_e32 v2, v2, v77
	v_lshlrev_b32_e32 v78, 16, v50
	v_and_b32_e32 v79, 0xffff0000, v50
	v_add_f32_e32 v2, v2, v78
	v_add_f32_e32 v2, v2, v79
	v_lshlrev_b32_e32 v80, 16, v51
	v_and_b32_e32 v81, 0xffff0000, v51
	v_add_f32_e32 v2, v2, v80
	v_add_f32_e32 v2, v2, v81
	s_mov_b32 s11, 0x31800000
	v_add_co_u32_e32 v72, vcc, s11, v72
	s_lshl_b64 s[6:7], s[6:7], 5
	s_waitcnt lgkmcnt(0)
	s_nop 1
	v_add_f32_dpp v57, v2, v2 quad_perm:[1,0,3,2] row_mask:0xf bank_mask:0xf bound_ctrl:1
	v_addc_co_u32_e32 v73, vcc, 0, v73, vcc
	v_lshl_add_u64 v[82:83], v[60:61], 0, s[6:7]
	global_load_dwordx4 v[48:51], v[72:73], off offset:2048
	global_load_dword v2, v[82:83], off
	s_waitcnt vmcnt(6)
	v_lshlrev_b32_e32 v72, 16, v41
	v_and_b32_e32 v73, 0xffff0000, v41
	s_waitcnt lgkmcnt(0)
	s_nop 1
	v_add_f32_dpp v41, v57, v57 quad_perm:[2,3,0,1] row_mask:0xf bank_mask:0xf bound_ctrl:1
	v_lshlrev_b32_e32 v82, 16, v37
	v_and_b32_e32 v83, 0xffff0000, v37
	v_pk_add_f32 v[72:73], v[72:73], v[82:83] neg_lo:[0,1] neg_hi:[0,1]
	s_mov_b32 s6, 0xf800000
	s_waitcnt lgkmcnt(0)
	s_nop 1
	v_add_f32_dpp v37, v41, v41 row_half_mirror row_mask:0xf bank_mask:0xf bound_ctrl:1
	v_pk_fma_f32 v[72:73], v[26:27], v[72:73], v[82:83]
	v_mul_f32_e32 v82, 0x3c800000, v37
	v_pk_add_f32 v[74:75], v[74:75], v[82:83] op_sel_hi:[1,0] neg_lo:[0,1] neg_hi:[0,1]
	v_pk_add_f32 v[76:77], v[76:77], v[82:83] op_sel_hi:[1,0] neg_lo:[0,1] neg_hi:[0,1]
	v_pk_mul_f32 v[84:85], v[74:75], v[74:75]
	v_pk_mul_f32 v[86:87], v[76:77], v[76:77]
	v_add_f32_e32 v37, v84, v85
	v_pk_add_f32 v[78:79], v[78:79], v[82:83] op_sel_hi:[1,0] neg_lo:[0,1] neg_hi:[0,1]
	v_add_f32_e32 v37, v86, v37
	v_pk_mul_f32 v[88:89], v[78:79], v[78:79]
	v_add_f32_e32 v37, v87, v37
	v_pk_add_f32 v[80:81], v[80:81], v[82:83] op_sel_hi:[1,0] neg_lo:[0,1] neg_hi:[0,1]
	v_add_f32_e32 v37, v88, v37
	v_pk_mul_f32 v[82:83], v[80:81], v[80:81]
	v_add_f32_e32 v37, v89, v37
	v_add_f32_e32 v37, v82, v37
	v_add_f32_e32 v37, v83, v37
	v_lshlrev_b32_e32 v86, 16, v38
	v_and_b32_e32 v87, 0xffff0000, v38
	v_lshlrev_b32_e32 v84, 16, v42
	v_and_b32_e32 v85, 0xffff0000, v42
	s_waitcnt lgkmcnt(0)
	s_nop 1
	v_add_f32_dpp v37, v37, v37 quad_perm:[1,0,3,2] row_mask:0xf bank_mask:0xf bound_ctrl:1
	s_waitcnt vmcnt(5)
	v_lshlrev_b32_e32 v82, 16, v45
	v_and_b32_e32 v83, 0xffff0000, v45
	v_pk_add_f32 v[84:85], v[84:85], v[86:87] neg_lo:[0,1] neg_hi:[0,1]
	v_lshlrev_b32_e32 v42, 16, v43
	s_waitcnt lgkmcnt(0)
	s_nop 1
	v_add_f32_dpp v37, v37, v37 quad_perm:[2,3,0,1] row_mask:0xf bank_mask:0xf bound_ctrl:1
	v_pk_fma_f32 v[84:85], v[20:21], v[84:85], v[86:87]
	v_lshlrev_b32_e32 v86, 16, v46
	v_and_b32_e32 v87, 0xffff0000, v46
	v_and_b32_e32 v43, 0xffff0000, v43
	s_waitcnt lgkmcnt(0)
	s_nop 1
	v_add_f32_dpp v37, v37, v37 row_half_mirror row_mask:0xf bank_mask:0xf bound_ctrl:1
	v_mov_b32_e32 v38, 0x3a27c5ac
	v_fmamk_f32 v37, v37, 0x3c800000, v38
	v_mul_f32_e32 v38, 0x4f800000, v37
	v_cmp_gt_f32_e32 vcc, s6, v37
	s_nop 1
	v_cndmask_b32_e32 v37, v37, v38, vcc
	v_sqrt_f32_e32 v41, v37
	v_lshlrev_b32_e32 v38, 16, v39
	v_and_b32_e32 v39, 0xffff0000, v39
	v_pk_add_f32 v[42:43], v[42:43], v[38:39] neg_lo:[0,1] neg_hi:[0,1]
	v_add_u32_e32 v45, -1, v41
	v_fma_f32 v46, -v45, v41, v37
	v_cmp_ge_f32_e64 s[6:7], 0, v46
	v_add_u32_e32 v46, 1, v41
	v_pk_fma_f32 v[38:39], v[22:23], v[42:43], v[38:39]
	v_cndmask_b32_e64 v45, v41, v45, s[6:7]
	v_fma_f32 v41, -v46, v41, v37
	v_cmp_lt_f32_e64 s[6:7], 0, v41
	v_lshlrev_b32_e32 v42, 16, v47
	v_and_b32_e32 v43, 0xffff0000, v47
	v_cndmask_b32_e64 v41, v45, v46, s[6:7]
	v_mul_f32_e32 v45, 0x37800000, v41
	v_cndmask_b32_e32 v41, v41, v45, vcc
	v_cmp_class_f32_e32 vcc, v37, v239
	s_nop 1
	v_cndmask_b32_e32 v37, v41, v37, vcc
	v_div_scale_f32 v41, s[6:7], v37, v37, 1.0
	v_rcp_f32_e32 v45, v41
	s_lshl_b64 s[6:7], s[8:9], 11
	v_fma_f32 v46, -v41, v45, 1.0
	v_fmac_f32_e32 v45, v46, v45
	v_div_scale_f32 v46, vcc, 1.0, v37, 1.0
	v_mul_f32_e32 v47, v46, v45
	v_fma_f32 v57, -v41, v47, v46
	v_fmac_f32_e32 v47, v57, v45
	v_fma_f32 v41, -v41, v47, v46
	v_div_fmas_f32 v41, v41, v45, v47
	v_div_fixup_f32 v46, v41, v37, 1.0
	v_pk_mul_f32 v[80:81], v[80:81], v[46:47] op_sel_hi:[1,0]
	s_andn2_b64 vcc, exec, s[12:13]
	v_pk_fma_f32 v[80:81], v[6:7], v[80:81], v[14:15]
	s_waitcnt vmcnt(4)
	v_pk_fma_f32 v[38:39], v[66:67], v[38:39], v[80:81] op_sel_hi:[0,1,1]
	v_pk_mul_f32 v[80:81], v[38:39], v[42:43]
	s_waitcnt vmcnt(3)
	v_lshlrev_b32_e32 v42, 16, v52
	v_pk_mul_f32 v[38:39], v[78:79], v[46:47] op_sel_hi:[1,0]
	v_and_b32_e32 v43, 0xffff0000, v52
	v_add_f32_e32 v37, 0, v42
	v_pk_fma_f32 v[38:39], v[4:5], v[38:39], v[12:13]
	v_add_f32_e32 v37, v37, v43
	v_lshlrev_b32_e32 v52, 16, v53
	v_pk_fma_f32 v[38:39], v[66:67], v[84:85], v[38:39] op_sel_hi:[0,1,1]
	v_and_b32_e32 v53, 0xffff0000, v53
	v_add_f32_e32 v37, v37, v52
	v_pk_mul_f32 v[78:79], v[38:39], v[86:87]
	v_pk_mul_f32 v[38:39], v[76:77], v[46:47] op_sel_hi:[1,0]
	v_add_f32_e32 v37, v37, v53
	v_lshlrev_b32_e32 v76, 16, v54
	v_and_b32_e32 v77, 0xffff0000, v54
	v_add_f32_e32 v37, v37, v76
	v_add_f32_e32 v37, v37, v77
	v_lshlrev_b32_e32 v54, 16, v55
	v_and_b32_e32 v55, 0xffff0000, v55
	v_add_f32_e32 v37, v37, v54
	v_add_f32_e32 v37, v37, v55
	v_pk_fma_f32 v[38:39], v[10:11], v[38:39], v[18:19]
	s_waitcnt lgkmcnt(0)
; __device__ __forceinline__ void unpack8(const u32x4 w, float (&f)[8]) { f[0] = bflo(w.x); f[1] = bfhi(w.x); f[2] = bflo(w.y); f[3] = bfhi(w.y); f[4] = bflo(w.z); f[5] = bfhi(w.z); f[6] = bflo(w.w); f[7] = bfhi(w.w); }
; __device__ __forceinline__ u32x4 pack8(const float (&f)[8]) { return (u32x4){pk2(f[0], f[1]), pk2(f[2], f[3]), pk2(f[4], f[5]), pk2(f[6], f[7])}; }
; __device__ __forceinline__ void post_phase(const KAS Args& a, LAS unsigned char* lds, int i, const int tid_, const int bid, const int nblk) {
;     ...
;           for (int k = 0; k < 2; ++k) { const int m = mb + k * stride;
;               float y[8], vc[8], vp[8], g[8], o[8];
;               unpack8(ry[k], y); unpack8(rvc[k], vc); unpack8(rvp[k], vp); unpack8(rg[k], g);
;               float s = 0.f;
; #pragma unroll
;               for (int e = 0; e < 8; ++e) s += y[e];
;               s += __shfl_xor(s, 1); s += __shfl_xor(s, 2); s += __shfl_xor(s, 4);
;               const float mean = s * (1.0f / 64.0f); float q = 0.f;
; #pragma unroll
;               for (int e = 0; e < 8; ++e) { const float d = y[e] - mean; q += d * d; }
;               q += __shfl_xor(q, 1); q += __shfl_xor(q, 2); q += __shfl_xor(q, 4);
;               const float rstd = 1.0f / sqrtf(q * (1.0f / 64.0f) + 64e-5f);
; #pragma unroll
;               for (int e = 0; e < 8; ++e) { const float vs = vc[e] + (vp[e] - vc[e]) * muv[e]; o[e] = ((y[e] - mean) * rstd * gg[e] + gb[e] + bon[k] * vs) * g[e]; }
;               if (has[k]) *(u32x4*)(Y + (size_t)m * D + c0) = pack8(o); } } }
	s_nop 1
	v_add_f32_dpp v37, v37, v37 quad_perm:[1,0,3,2] row_mask:0xf bank_mask:0xf bound_ctrl:1
	v_pk_fma_f32 v[38:39], v[66:67], v[72:73], v[38:39] op_sel_hi:[0,1,1]
	v_pk_mul_f32 v[72:73], v[38:39], v[82:83]
	v_pk_mul_f32 v[38:39], v[74:75], v[46:47] op_sel_hi:[1,0]
	v_lshlrev_b32_e32 v46, 16, v40
	s_waitcnt lgkmcnt(0)
	s_nop 1
	v_add_f32_dpp v45, v37, v37 quad_perm:[2,3,0,1] row_mask:0xf bank_mask:0xf bound_ctrl:1
	v_and_b32_e32 v47, 0xffff0000, v40
	v_lshlrev_b32_e32 v40, 16, v36
	v_and_b32_e32 v41, 0xffff0000, v36
	v_pk_add_f32 v[36:37], v[46:47], v[40:41] neg_lo:[0,1] neg_hi:[0,1]
	v_pk_fma_f32 v[38:39], v[8:9], v[38:39], v[16:17]
	v_pk_fma_f32 v[36:37], v[24:25], v[36:37], v[40:41]
	v_lshlrev_b32_e32 v74, 16, v44
	v_pk_fma_f32 v[46:47], v[66:67], v[36:37], v[38:39] op_sel_hi:[0,1,1]
	s_waitcnt lgkmcnt(0)
	s_nop 1
	v_add_f32_dpp v36, v45, v45 row_half_mirror row_mask:0xf bank_mask:0xf bound_ctrl:1
	v_mul_f32_e32 v66, 0x3c800000, v36
	v_pk_add_f32 v[36:37], v[42:43], v[66:67] op_sel_hi:[1,0] neg_lo:[0,1] neg_hi:[0,1]
	v_pk_add_f32 v[38:39], v[52:53], v[66:67] op_sel_hi:[1,0] neg_lo:[0,1] neg_hi:[0,1]
	v_pk_mul_f32 v[82:83], v[36:37], v[36:37]
	v_pk_mul_f32 v[52:53], v[38:39], v[38:39]
	v_add_f32_e32 v45, v82, v83
	v_pk_add_f32 v[40:41], v[76:77], v[66:67] op_sel_hi:[1,0] neg_lo:[0,1] neg_hi:[0,1]
	v_add_f32_e32 v45, v52, v45
	v_pk_mul_f32 v[76:77], v[40:41], v[40:41]
	v_add_f32_e32 v45, v53, v45
	v_pk_add_f32 v[42:43], v[54:55], v[66:67] op_sel_hi:[1,0] neg_lo:[0,1] neg_hi:[0,1]
	v_add_f32_e32 v45, v76, v45
	v_pk_mul_f32 v[54:55], v[42:43], v[42:43]
	v_add_f32_e32 v45, v77, v45
	v_add_f32_e32 v45, v54, v45
	v_add_f32_e32 v54, v55, v45
	v_and_b32_e32 v75, 0xffff0000, v44
	v_pk_mul_f32 v[44:45], v[46:47], v[74:75]
	v_cvt_pk_bf16_f32 v53, v72, v73
	v_cvt_pk_bf16_f32 v52, v44, v45
	s_waitcnt lgkmcnt(0)
	s_nop 1
	v_add_f32_dpp v44, v54, v54 quad_perm:[1,0,3,2] row_mask:0xf bank_mask:0xf bound_ctrl:1
	v_cvt_pk_bf16_f32 v54, v78, v79
	v_cvt_pk_bf16_f32 v55, v80, v81
	v_lshl_add_u64 v[46:47], v[62:63], 0, s[6:7]
	global_store_dwordx4 v[46:47], v[52:55], off
	s_waitcnt lgkmcnt(0)
	s_nop 1
	v_add_f32_dpp v44, v44, v44 quad_perm:[2,3,0,1] row_mask:0xf bank_mask:0xf bound_ctrl:1
	ds_bpermute_b32 v45, v70, v44
	s_cbranch_vccnz .LBB0_141
	s_waitcnt lgkmcnt(0)
	v_add_f32_e32 v44, v44, v45
	v_mov_b32_e32 v45, 0x3a27c5ac
	v_fmamk_f32 v44, v44, 0x3c800000, v45
	s_mov_b32 s6, 0xf800000
	v_mul_f32_e32 v45, 0x4f800000, v44
	v_cmp_gt_f32_e32 vcc, s6, v44
	s_ashr_i32 s11, s10, 31
	s_nop 0
	v_cndmask_b32_e32 v44, v44, v45, vcc
	v_sqrt_f32_e32 v45, v44
	s_nop 0
	v_add_u32_e32 v46, -1, v45
	v_fma_f32 v52, -v46, v45, v44
	v_add_u32_e32 v47, 1, v45
	v_cmp_ge_f32_e64 s[6:7], 0, v52
	s_nop 1
	v_cndmask_b32_e64 v46, v45, v46, s[6:7]
	v_fma_f32 v45, -v47, v45, v44
	v_cmp_lt_f32_e64 s[6:7], 0, v45
	s_nop 1
	v_cndmask_b32_e64 v45, v46, v47, s[6:7]
	v_mul_f32_e32 v46, 0x37800000, v45
	v_cndmask_b32_e32 v45, v45, v46, vcc
	v_cmp_class_f32_e32 vcc, v44, v239
	s_nop 1
	v_cndmask_b32_e32 v44, v45, v44, vcc
	v_div_scale_f32 v45, s[6:7], v44, v44, 1.0
	v_rcp_f32_e32 v46, v45
	s_lshl_b64 s[6:7], s[10:11], 11
	v_fma_f32 v47, -v45, v46, 1.0
	v_fmac_f32_e32 v46, v47, v46
	v_div_scale_f32 v47, vcc, 1.0, v44, 1.0
	v_mul_f32_e32 v52, v47, v46
	v_fma_f32 v53, -v45, v52, v47
	v_fmac_f32_e32 v52, v53, v46
	v_fma_f32 v45, -v45, v52, v47
	v_div_fmas_f32 v45, v45, v46, v52
	v_div_fixup_f32 v44, v45, v44, 1.0
	s_waitcnt vmcnt(3)
	v_lshlrev_b32_e32 v46, 16, v35
	v_and_b32_e32 v47, 0xffff0000, v35
	v_lshlrev_b32_e32 v52, 16, v31
	v_and_b32_e32 v53, 0xffff0000, v31
	v_pk_mul_f32 v[42:43], v[42:43], v[44:45] op_sel_hi:[1,0]
	v_pk_add_f32 v[46:47], v[46:47], v[52:53] neg_lo:[0,1] neg_hi:[0,1]
	v_pk_fma_f32 v[42:43], v[6:7], v[42:43], v[14:15]
	v_pk_fma_f32 v[46:47], v[22:23], v[46:47], v[52:53]
	v_and_b32_e32 v35, 0xffff0000, v30
	s_waitcnt vmcnt(1)
	v_pk_fma_f32 v[42:43], v[2:3], v[46:47], v[42:43] op_sel_hi:[0,1,1]
	v_lshlrev_b32_e32 v46, 16, v51
	v_and_b32_e32 v47, 0xffff0000, v51
	v_pk_mul_f32 v[42:43], v[42:43], v[46:47]
	v_lshlrev_b32_e32 v46, 16, v34
	v_and_b32_e32 v47, 0xffff0000, v34
	v_lshlrev_b32_e32 v34, 16, v30
	v_pk_mul_f32 v[40:41], v[40:41], v[44:45] op_sel_hi:[1,0]
	v_pk_add_f32 v[30:31], v[46:47], v[34:35] neg_lo:[0,1] neg_hi:[0,1]
	v_pk_fma_f32 v[40:41], v[4:5], v[40:41], v[12:13]
	v_pk_fma_f32 v[30:31], v[20:21], v[30:31], v[34:35]
	v_lshlrev_b32_e32 v34, 16, v50
	v_pk_fma_f32 v[30:31], v[2:3], v[30:31], v[40:41] op_sel_hi:[0,1,1]
	v_and_b32_e32 v35, 0xffff0000, v50
	v_pk_mul_f32 v[30:31], v[30:31], v[34:35]
	v_pk_mul_f32 v[34:35], v[38:39], v[44:45] op_sel_hi:[1,0]
	v_lshlrev_b32_e32 v38, 16, v33
	v_and_b32_e32 v39, 0xffff0000, v33
	v_lshlrev_b32_e32 v40, 16, v29
	v_and_b32_e32 v41, 0xffff0000, v29
	v_pk_add_f32 v[38:39], v[38:39], v[40:41] neg_lo:[0,1] neg_hi:[0,1]
	v_pk_fma_f32 v[34:35], v[10:11], v[34:35], v[18:19]
	v_pk_fma_f32 v[38:39], v[26:27], v[38:39], v[40:41]
	v_and_b32_e32 v33, 0xffff0000, v28
	v_pk_fma_f32 v[34:35], v[2:3], v[38:39], v[34:35] op_sel_hi:[0,1,1]
	v_lshlrev_b32_e32 v38, 16, v49
	v_and_b32_e32 v39, 0xffff0000, v49
	v_pk_mul_f32 v[34:35], v[34:35], v[38:39]
	v_lshlrev_b32_e32 v38, 16, v32
	v_and_b32_e32 v39, 0xffff0000, v32
	v_lshlrev_b32_e32 v32, 16, v28
	v_pk_mul_f32 v[36:37], v[36:37], v[44:45] op_sel_hi:[1,0]
	v_pk_add_f32 v[28:29], v[38:39], v[32:33] neg_lo:[0,1] neg_hi:[0,1]
	v_pk_fma_f32 v[36:37], v[8:9], v[36:37], v[16:17]
	v_pk_fma_f32 v[28:29], v[24:25], v[28:29], v[32:33]
	v_lshlrev_b32_e32 v32, 16, v48
	v_pk_fma_f32 v[28:29], v[2:3], v[28:29], v[36:37] op_sel_hi:[0,1,1]
	v_and_b32_e32 v33, 0xffff0000, v48
	v_pk_mul_f32 v[28:29], v[28:29], v[32:33]
	v_cvt_pk_bf16_f32 v30, v30, v31
	v_cvt_pk_bf16_f32 v28, v28, v29
	v_cvt_pk_bf16_f32 v29, v34, v35
	v_cvt_pk_bf16_f32 v31, v42, v43
	v_lshl_add_u64 v[32:33], v[62:63], 0, s[6:7]
	global_store_dwordx4 v[32:33], v[28:31], off
	s_branch .LBB0_141

; __device__ __forceinline__ void unpack8(const u32x4 w, float (&f)[8]) { f[0] = bflo(w.x); f[1] = bfhi(w.x); f[2] = bflo(w.y); f[3] = bfhi(w.y); f[4] = bflo(w.z); f[5] = bfhi(w.z); f[6] = bflo(w.w); f[7] = bfhi(w.w); }
; __device__ __forceinline__ float wave_sum(float v) {
; #pragma unroll
;     for (int o = 1; o < 64; o <<= 1) v += __shfl_xor(v, o);
;     return v;
; }
; __device__ __forceinline__ void post_phase(const KAS Args& a, LAS unsigned char* lds, int i, const int tid_, const int bid, const int nblk) {
;     ...
;             for (int k = 0; k < 4; ++k) { const int tok = wave * 16 + tb + k; float sv[8]; unpack8(raw[k], sv); float s = 0.f;
; #pragma unroll
;                 for (int e = 0; e < 8; ++e) s += sv[e];
;                 const float mean = wave_sum(s) * (1.0f / 512.0f); float q = 0.f;
; #pragma unroll
;                 for (int e = 0; e < 8; ++e) { const float d = sv[e] - mean; q += d * d; }
;                 const float rstd = 1.0f / sqrtf(wave_sum(q) * (1.0f / 512.0f) + 1e-5f);
;                 if (lane == 0) { stat[2 * tok] = mean; stat[2 * tok + 1] = rstd; } } }
.LBB0_155:
	v_add_co_u32_e32 v4, vcc, 0xffffc000, v16
	s_waitcnt lgkmcnt(0)
	s_nop 0
	v_addc_co_u32_e32 v5, vcc, -1, v17, vcc
	global_load_dwordx4 v[4:7], v[4:5], off offset:-512
	v_add_co_u32_e32 v8, vcc, 0xffffe000, v16
	s_nop 1
	v_addc_co_u32_e32 v9, vcc, -1, v17, vcc
	global_load_dwordx4 v[12:15], v[8:9], off offset:-3072
	s_waitcnt vmcnt(1)
	v_lshlrev_b32_e32 v18, 16, v4
	v_and_b32_e32 v19, 0xffff0000, v4
	v_add_f32_e32 v2, 0, v18
	v_lshlrev_b32_e32 v20, 16, v5
	v_add_f32_e32 v2, v2, v19
	v_and_b32_e32 v21, 0xffff0000, v5
	v_add_f32_e32 v2, v2, v20
	v_lshlrev_b32_e32 v22, 16, v6
	v_add_f32_e32 v2, v2, v21
	v_and_b32_e32 v23, 0xffff0000, v6
	v_add_f32_e32 v2, v2, v22
	v_lshlrev_b32_e32 v24, 16, v7
	v_add_f32_e32 v2, v2, v23
	v_and_b32_e32 v25, 0xffff0000, v7
	v_add_f32_e32 v2, v2, v24
	v_add_f32_e32 v2, v2, v25
	v_add_co_u32_e32 v4, vcc, 0xfffff000, v16
	s_waitcnt lgkmcnt(0)
	s_nop 1
	v_add_f32_dpp v2, v2, v2 quad_perm:[1,0,3,2] row_mask:0xf bank_mask:0xf bound_ctrl:1
	v_addc_co_u32_e32 v5, vcc, -1, v17, vcc
	global_load_dwordx4 v[8:11], v[4:5], off offset:-1536
	s_nop 0
	global_load_dwordx4 v[4:7], v[16:17], off
	s_waitcnt lgkmcnt(0)
	s_nop 1
	v_add_f32_dpp v2, v2, v2 quad_perm:[2,3,0,1] row_mask:0xf bank_mask:0xf bound_ctrl:1
	s_waitcnt lgkmcnt(0)
	s_nop 1
	v_add_f32_dpp v2, v2, v2 row_half_mirror row_mask:0xf bank_mask:0xf bound_ctrl:1
	s_waitcnt lgkmcnt(0)
	s_nop 1
	v_add_f32_dpp v2, v2, v2 row_ror:8 row_mask:0xf bank_mask:0xf bound_ctrl:1
	s_waitcnt lgkmcnt(0)
	v_mov_b32_e32 v26, v2
	s_nop 1
	v_permlane16_swap_b32_e32 v2, v26
	v_add_f32_e32 v2, v2, v26
	s_waitcnt lgkmcnt(0)
	v_mov_b32_e32 v26, v2
	s_nop 1
	v_permlane32_swap_b32_e32 v2, v26
	v_add_f32_e32 v2, v2, v26
	v_fmac_f32_e32 v19, 0xbb000000, v2
	v_fmac_f32_e32 v18, 0xbb000000, v2
	v_mul_f32_e32 v19, v19, v19
	v_fmac_f32_e32 v20, 0xbb000000, v2
	v_fmac_f32_e32 v19, v18, v18
	v_fmac_f32_e32 v21, 0xbb000000, v2
	v_fmac_f32_e32 v19, v20, v20
	v_fmac_f32_e32 v22, 0xbb000000, v2
	v_fmac_f32_e32 v19, v21, v21
	v_fmac_f32_e32 v23, 0xbb000000, v2
	v_fmac_f32_e32 v19, v22, v22
	v_fmac_f32_e32 v24, 0xbb000000, v2
	v_fmac_f32_e32 v19, v23, v23
	v_fmac_f32_e32 v19, v24, v24
	v_fmac_f32_e32 v25, 0xbb000000, v2
	v_fmac_f32_e32 v19, v25, v25
	s_waitcnt lgkmcnt(0)
	s_nop 1
	v_add_f32_dpp v18, v19, v19 quad_perm:[1,0,3,2] row_mask:0xf bank_mask:0xf bound_ctrl:1
	s_waitcnt lgkmcnt(0)
	s_nop 1
	v_add_f32_dpp v18, v18, v18 quad_perm:[2,3,0,1] row_mask:0xf bank_mask:0xf bound_ctrl:1
	s_waitcnt lgkmcnt(0)
	s_nop 1
	v_add_f32_dpp v18, v18, v18 row_half_mirror row_mask:0xf bank_mask:0xf bound_ctrl:1
	s_waitcnt lgkmcnt(0)
	s_nop 1
	v_add_f32_dpp v18, v18, v18 row_ror:8 row_mask:0xf bank_mask:0xf bound_ctrl:1
	s_waitcnt lgkmcnt(0)
	v_mov_b32_e32 v19, v18
	s_nop 1
	v_permlane16_swap_b32_e32 v18, v19
	v_add_f32_e32 v18, v18, v19
	ds_bpermute_b32 v19, v129, v18
	s_and_saveexec_b64 s[2:3], s[6:7]
	s_cbranch_execz .LBB0_157
	s_waitcnt lgkmcnt(0)
	v_add_f32_e32 v18, v18, v19
	v_fmamk_f32 v18, v18, 0x3b000000, v240
	s_mov_b32 s0, 0xf800000
	v_mul_f32_e32 v19, 0x4f800000, v18
	v_cmp_gt_f32_e32 vcc, s0, v18
	v_mul_f32_e32 v2, 0x3b000000, v2
	s_nop 0
	v_cndmask_b32_e32 v18, v18, v19, vcc
	v_sqrt_f32_e32 v19, v18
	s_nop 0
	v_add_u32_e32 v20, -1, v19
	v_fma_f32 v22, -v20, v19, v18
	v_add_u32_e32 v21, 1, v19
	v_cmp_ge_f32_e64 s[76:77], 0, v22
	s_nop 1
	v_cndmask_b32_e64 v20, v19, v20, s[76:77]
	v_fma_f32 v19, -v21, v19, v18
	v_cmp_lt_f32_e64 s[76:77], 0, v19
	s_nop 1
	v_cndmask_b32_e64 v19, v20, v21, s[76:77]
	v_mul_f32_e32 v20, 0x37800000, v19
	v_cndmask_b32_e32 v19, v19, v20, vcc
	v_cmp_class_f32_e32 vcc, v18, v239
	s_nop 1
	v_cndmask_b32_e32 v18, v19, v18, vcc
	v_div_scale_f32 v19, s[76:77], v18, v18, 1.0
	v_rcp_f32_e32 v20, v19
	s_nop 0
	v_fma_f32 v21, -v19, v20, 1.0
	v_fmac_f32_e32 v20, v21, v20
	v_div_scale_f32 v21, vcc, 1.0, v18, 1.0
	v_mul_f32_e32 v22, v21, v20
	v_fma_f32 v23, -v19, v22, v21
	v_fmac_f32_e32 v22, v23, v20
	v_fma_f32 v19, -v19, v22, v21
	v_div_fmas_f32 v19, v19, v20, v22
	v_div_fixup_f32 v18, v19, v18, 1.0
	v_mov_b32_e32 v19, s92
	ds_write2_b32 v19, v2, v18 offset1:1
.LBB0_157:
	s_or_b64 exec, exec, s[2:3]
	s_waitcnt vmcnt(2)
	v_lshlrev_b32_e32 v18, 16, v12
	v_and_b32_e32 v12, 0xffff0000, v12
	v_add_f32_e32 v2, 0, v18
	s_waitcnt lgkmcnt(0)
	v_lshlrev_b32_e32 v19, 16, v13
	v_add_f32_e32 v2, v2, v12
	v_and_b32_e32 v13, 0xffff0000, v13
	v_add_f32_e32 v2, v2, v19
	v_lshlrev_b32_e32 v20, 16, v14
	v_add_f32_e32 v2, v2, v13
	v_and_b32_e32 v14, 0xffff0000, v14
	v_add_f32_e32 v2, v2, v20
	v_lshlrev_b32_e32 v21, 16, v15
	v_add_f32_e32 v2, v2, v14
	v_and_b32_e32 v15, 0xffff0000, v15
	v_add_f32_e32 v2, v2, v21
	v_add_f32_e32 v2, v2, v15
	s_waitcnt lgkmcnt(0)
	s_nop 1
	v_add_f32_dpp v2, v2, v2 quad_perm:[1,0,3,2] row_mask:0xf bank_mask:0xf bound_ctrl:1
	s_waitcnt lgkmcnt(0)
	s_nop 1
	v_add_f32_dpp v2, v2, v2 quad_perm:[2,3,0,1] row_mask:0xf bank_mask:0xf bound_ctrl:1
	s_waitcnt lgkmcnt(0)
	s_nop 1
	v_add_f32_dpp v2, v2, v2 row_half_mirror row_mask:0xf bank_mask:0xf bound_ctrl:1
	s_waitcnt lgkmcnt(0)
	s_nop 1
	v_add_f32_dpp v2, v2, v2 row_ror:8 row_mask:0xf bank_mask:0xf bound_ctrl:1
	s_waitcnt lgkmcnt(0)
	v_mov_b32_e32 v22, v2
	s_nop 1
	v_permlane16_swap_b32_e32 v2, v22
	v_add_f32_e32 v2, v2, v22
	s_waitcnt lgkmcnt(0)
	v_mov_b32_e32 v22, v2
	s_nop 1
	v_permlane32_swap_b32_e32 v2, v22
	v_add_f32_e32 v2, v2, v22
	v_fmac_f32_e32 v12, 0xbb000000, v2
	v_fmac_f32_e32 v18, 0xbb000000, v2
	v_mul_f32_e32 v12, v12, v12
	v_fmac_f32_e32 v19, 0xbb000000, v2
	v_fmac_f32_e32 v12, v18, v18
	v_fmac_f32_e32 v13, 0xbb000000, v2
	v_fmac_f32_e32 v12, v19, v19
	v_fmac_f32_e32 v20, 0xbb000000, v2
	v_fmac_f32_e32 v12, v13, v13
	v_fmac_f32_e32 v14, 0xbb000000, v2
	v_fmac_f32_e32 v12, v20, v20
	v_fmac_f32_e32 v21, 0xbb000000, v2
	v_fmac_f32_e32 v12, v14, v14
	v_fmac_f32_e32 v12, v21, v21
	v_fmac_f32_e32 v15, 0xbb000000, v2
	v_fmac_f32_e32 v12, v15, v15
	s_waitcnt lgkmcnt(0)
	s_nop 1
	v_add_f32_dpp v12, v12, v12 quad_perm:[1,0,3,2] row_mask:0xf bank_mask:0xf bound_ctrl:1
	s_waitcnt lgkmcnt(0)
	s_nop 1
	v_add_f32_dpp v12, v12, v12 quad_perm:[2,3,0,1] row_mask:0xf bank_mask:0xf bound_ctrl:1
	s_waitcnt lgkmcnt(0)
	s_nop 1
	v_add_f32_dpp v12, v12, v12 row_half_mirror row_mask:0xf bank_mask:0xf bound_ctrl:1
	s_waitcnt lgkmcnt(0)
	s_nop 1
	v_add_f32_dpp v12, v12, v12 row_ror:8 row_mask:0xf bank_mask:0xf bound_ctrl:1
	s_waitcnt lgkmcnt(0)
	v_mov_b32_e32 v13, v12
	s_nop 1
	v_permlane16_swap_b32_e32 v12, v13
	v_add_f32_e32 v12, v12, v13
	ds_bpermute_b32 v13, v129, v12
	s_and_saveexec_b64 s[2:3], s[6:7]
	s_cbranch_execz .LBB0_159
; __device__ __forceinline__ void unpack8(const u32x4 w, float (&f)[8]) { f[0] = bflo(w.x); f[1] = bfhi(w.x); f[2] = bflo(w.y); f[3] = bfhi(w.y); f[4] = bflo(w.z); f[5] = bfhi(w.z); f[6] = bflo(w.w); f[7] = bfhi(w.w); }
; __device__ __forceinline__ float wave_sum(float v) {
; #pragma unroll
;     for (int o = 1; o < 64; o <<= 1) v += __shfl_xor(v, o);
;     return v;
; }
; __device__ __forceinline__ void post_phase(const KAS Args& a, LAS unsigned char* lds, int i, const int tid_, const int bid, const int nblk) {
;     ...
;             for (int k = 0; k < 4; ++k) { const int tok = wave * 16 + tb + k; float sv[8]; unpack8(raw[k], sv); float s = 0.f;
; #pragma unroll
;                 for (int e = 0; e < 8; ++e) s += sv[e];
;                 const float mean = wave_sum(s) * (1.0f / 512.0f); float q = 0.f;
; #pragma unroll
;                 for (int e = 0; e < 8; ++e) { const float d = sv[e] - mean; q += d * d; }
;                 const float rstd = 1.0f / sqrtf(wave_sum(q) * (1.0f / 512.0f) + 1e-5f);
;                 if (lane == 0) { stat[2 * tok] = mean; stat[2 * tok + 1] = rstd; } } }
	s_waitcnt lgkmcnt(0)
	v_add_f32_e32 v12, v12, v13
	v_fmamk_f32 v12, v12, 0x3b000000, v240
	s_mov_b32 s0, 0xf800000
	v_mul_f32_e32 v13, 0x4f800000, v12
	v_cmp_gt_f32_e32 vcc, s0, v12
	v_mul_f32_e32 v2, 0x3b000000, v2
	s_nop 0
	v_cndmask_b32_e32 v12, v12, v13, vcc
	v_sqrt_f32_e32 v13, v12
	s_nop 0
	v_add_u32_e32 v14, -1, v13
	v_fma_f32 v18, -v14, v13, v12
	v_add_u32_e32 v15, 1, v13
	v_cmp_ge_f32_e64 s[76:77], 0, v18
	s_nop 1
	v_cndmask_b32_e64 v14, v13, v14, s[76:77]
	v_fma_f32 v13, -v15, v13, v12
	v_cmp_lt_f32_e64 s[76:77], 0, v13
	s_nop 1
	v_cndmask_b32_e64 v13, v14, v15, s[76:77]
	v_mul_f32_e32 v14, 0x37800000, v13
	v_cndmask_b32_e32 v13, v13, v14, vcc
	v_cmp_class_f32_e32 vcc, v12, v239
	s_nop 1
	v_cndmask_b32_e32 v12, v13, v12, vcc
	v_div_scale_f32 v13, s[76:77], v12, v12, 1.0
	v_rcp_f32_e32 v14, v13
	s_nop 0
	v_fma_f32 v15, -v13, v14, 1.0
	v_fmac_f32_e32 v14, v15, v14
	v_div_scale_f32 v15, vcc, 1.0, v12, 1.0
	v_mul_f32_e32 v18, v15, v14
	v_fma_f32 v19, -v13, v18, v15
	v_fmac_f32_e32 v18, v19, v14
	v_fma_f32 v13, -v13, v18, v15
	v_div_fmas_f32 v13, v13, v14, v18
	v_div_fixup_f32 v12, v13, v12, 1.0
	v_mov_b32_e32 v13, s92
	ds_write2_b32 v13, v2, v12 offset0:2 offset1:3
.LBB0_159:
	s_or_b64 exec, exec, s[2:3]
	s_waitcnt vmcnt(1)
	v_lshlrev_b32_e32 v12, 16, v8
	v_and_b32_e32 v8, 0xffff0000, v8
	v_add_f32_e32 v2, 0, v12
	s_waitcnt lgkmcnt(0)
	v_lshlrev_b32_e32 v13, 16, v9
	v_add_f32_e32 v2, v2, v8
	v_and_b32_e32 v9, 0xffff0000, v9
	v_add_f32_e32 v2, v2, v13
	v_lshlrev_b32_e32 v14, 16, v10
	v_add_f32_e32 v2, v2, v9
	v_and_b32_e32 v10, 0xffff0000, v10
	v_add_f32_e32 v2, v2, v14
	v_lshlrev_b32_e32 v15, 16, v11
	v_add_f32_e32 v2, v2, v10
	v_and_b32_e32 v11, 0xffff0000, v11
	v_add_f32_e32 v2, v2, v15
	v_add_f32_e32 v2, v2, v11
	s_waitcnt lgkmcnt(0)
	s_nop 1
	v_add_f32_dpp v2, v2, v2 quad_perm:[1,0,3,2] row_mask:0xf bank_mask:0xf bound_ctrl:1
	s_waitcnt lgkmcnt(0)
	s_nop 1
	v_add_f32_dpp v2, v2, v2 quad_perm:[2,3,0,1] row_mask:0xf bank_mask:0xf bound_ctrl:1
	s_waitcnt lgkmcnt(0)
	s_nop 1
	v_add_f32_dpp v2, v2, v2 row_half_mirror row_mask:0xf bank_mask:0xf bound_ctrl:1
	s_waitcnt lgkmcnt(0)
	s_nop 1
	v_add_f32_dpp v2, v2, v2 row_ror:8 row_mask:0xf bank_mask:0xf bound_ctrl:1
	s_waitcnt lgkmcnt(0)
	v_mov_b32_e32 v18, v2
	s_nop 1
	v_permlane16_swap_b32_e32 v2, v18
	v_add_f32_e32 v2, v2, v18
	s_waitcnt lgkmcnt(0)
	v_mov_b32_e32 v18, v2
	s_nop 1
	v_permlane32_swap_b32_e32 v2, v18
	v_add_f32_e32 v2, v2, v18
	v_fmac_f32_e32 v8, 0xbb000000, v2
	v_fmac_f32_e32 v12, 0xbb000000, v2
	v_mul_f32_e32 v8, v8, v8
	v_fmac_f32_e32 v13, 0xbb000000, v2
	v_fmac_f32_e32 v8, v12, v12
	v_fmac_f32_e32 v9, 0xbb000000, v2
	v_fmac_f32_e32 v8, v13, v13
	v_fmac_f32_e32 v14, 0xbb000000, v2
	v_fmac_f32_e32 v8, v9, v9
	v_fmac_f32_e32 v10, 0xbb000000, v2
	v_fmac_f32_e32 v8, v14, v14
	v_fmac_f32_e32 v15, 0xbb000000, v2
	v_fmac_f32_e32 v8, v10, v10
	v_fmac_f32_e32 v8, v15, v15
	v_fmac_f32_e32 v11, 0xbb000000, v2
	v_fmac_f32_e32 v8, v11, v11
	s_waitcnt lgkmcnt(0)
	s_nop 1
	v_add_f32_dpp v8, v8, v8 quad_perm:[1,0,3,2] row_mask:0xf bank_mask:0xf bound_ctrl:1
	s_waitcnt lgkmcnt(0)
	s_nop 1
	v_add_f32_dpp v8, v8, v8 quad_perm:[2,3,0,1] row_mask:0xf bank_mask:0xf bound_ctrl:1
	s_waitcnt lgkmcnt(0)
	s_nop 1
	v_add_f32_dpp v8, v8, v8 row_half_mirror row_mask:0xf bank_mask:0xf bound_ctrl:1
	s_waitcnt lgkmcnt(0)
	s_nop 1
	v_add_f32_dpp v8, v8, v8 row_ror:8 row_mask:0xf bank_mask:0xf bound_ctrl:1
	s_waitcnt lgkmcnt(0)
	v_mov_b32_e32 v9, v8
	s_nop 1
	v_permlane16_swap_b32_e32 v8, v9
	v_add_f32_e32 v8, v8, v9
	ds_bpermute_b32 v9, v129, v8
	s_and_saveexec_b64 s[2:3], s[6:7]
	s_cbranch_execz .LBB0_161
	s_waitcnt lgkmcnt(0)
	v_add_f32_e32 v8, v8, v9
	v_fmamk_f32 v8, v8, 0x3b000000, v240
	s_mov_b32 s0, 0xf800000
	v_mul_f32_e32 v9, 0x4f800000, v8
	v_cmp_gt_f32_e32 vcc, s0, v8
	v_mul_f32_e32 v2, 0x3b000000, v2
	s_nop 0
	v_cndmask_b32_e32 v8, v8, v9, vcc
	v_sqrt_f32_e32 v9, v8
	s_nop 0
	v_add_u32_e32 v10, -1, v9
	v_fma_f32 v12, -v10, v9, v8
	v_add_u32_e32 v11, 1, v9
	v_cmp_ge_f32_e64 s[76:77], 0, v12
	s_nop 1
	v_cndmask_b32_e64 v10, v9, v10, s[76:77]
	v_fma_f32 v9, -v11, v9, v8
	v_cmp_lt_f32_e64 s[76:77], 0, v9
	s_nop 1
	v_cndmask_b32_e64 v9, v10, v11, s[76:77]
	v_mul_f32_e32 v10, 0x37800000, v9
	v_cndmask_b32_e32 v9, v9, v10, vcc
	v_cmp_class_f32_e32 vcc, v8, v239
	s_nop 1
	v_cndmask_b32_e32 v8, v9, v8, vcc
	v_div_scale_f32 v9, s[76:77], v8, v8, 1.0
	v_rcp_f32_e32 v10, v9
	s_nop 0
	v_fma_f32 v11, -v9, v10, 1.0
	v_fmac_f32_e32 v10, v11, v10
	v_div_scale_f32 v11, vcc, 1.0, v8, 1.0
	v_mul_f32_e32 v12, v11, v10
	v_fma_f32 v13, -v9, v12, v11
	v_fmac_f32_e32 v12, v13, v10
	v_fma_f32 v9, -v9, v12, v11
	v_div_fmas_f32 v9, v9, v10, v12
	v_div_fixup_f32 v8, v9, v8, 1.0
	v_mov_b32_e32 v9, s92
	ds_write2_b32 v9, v2, v8 offset0:4 offset1:5
; __device__ __forceinline__ void unpack8(const u32x4 w, float (&f)[8]) { f[0] = bflo(w.x); f[1] = bfhi(w.x); f[2] = bflo(w.y); f[3] = bfhi(w.y); f[4] = bflo(w.z); f[5] = bfhi(w.z); f[6] = bflo(w.w); f[7] = bfhi(w.w); }
; __device__ __forceinline__ float wave_sum(float v) {
; #pragma unroll
;     for (int o = 1; o < 64; o <<= 1) v += __shfl_xor(v, o);
;     return v;
; }
; __device__ __forceinline__ void post_phase(const KAS Args& a, LAS unsigned char* lds, int i, const int tid_, const int bid, const int nblk) {
;     ...
;             for (int k = 0; k < 4; ++k) { const int tok = wave * 16 + tb + k; float sv[8]; unpack8(raw[k], sv); float s = 0.f;
; #pragma unroll
;                 for (int e = 0; e < 8; ++e) s += sv[e];
;                 const float mean = wave_sum(s) * (1.0f / 512.0f); float q = 0.f;
; #pragma unroll
;                 for (int e = 0; e < 8; ++e) { const float d = sv[e] - mean; q += d * d; }
;                 const float rstd = 1.0f / sqrtf(wave_sum(q) * (1.0f / 512.0f) + 1e-5f);
;                 if (lane == 0) { stat[2 * tok] = mean; stat[2 * tok + 1] = rstd; } } }
.LBB0_161:
	s_or_b64 exec, exec, s[2:3]
	s_waitcnt vmcnt(0)
	v_lshlrev_b32_e32 v8, 16, v4
	v_and_b32_e32 v4, 0xffff0000, v4
	v_add_f32_e32 v2, 0, v8
	s_waitcnt lgkmcnt(0)
	v_lshlrev_b32_e32 v9, 16, v5
	v_add_f32_e32 v2, v2, v4
	v_and_b32_e32 v5, 0xffff0000, v5
	v_add_f32_e32 v2, v2, v9
	v_lshlrev_b32_e32 v10, 16, v6
	v_add_f32_e32 v2, v2, v5
	v_and_b32_e32 v6, 0xffff0000, v6
	v_add_f32_e32 v2, v2, v10
	v_lshlrev_b32_e32 v11, 16, v7
	v_add_f32_e32 v2, v2, v6
	v_and_b32_e32 v7, 0xffff0000, v7
	v_add_f32_e32 v2, v2, v11
	v_add_f32_e32 v2, v2, v7
	s_waitcnt lgkmcnt(0)
	s_nop 1
	v_add_f32_dpp v2, v2, v2 quad_perm:[1,0,3,2] row_mask:0xf bank_mask:0xf bound_ctrl:1
	s_waitcnt lgkmcnt(0)
	s_nop 1
	v_add_f32_dpp v2, v2, v2 quad_perm:[2,3,0,1] row_mask:0xf bank_mask:0xf bound_ctrl:1
	s_waitcnt lgkmcnt(0)
	s_nop 1
	v_add_f32_dpp v2, v2, v2 row_half_mirror row_mask:0xf bank_mask:0xf bound_ctrl:1
	s_waitcnt lgkmcnt(0)
	s_nop 1
	v_add_f32_dpp v2, v2, v2 row_ror:8 row_mask:0xf bank_mask:0xf bound_ctrl:1
	s_waitcnt lgkmcnt(0)
	v_mov_b32_e32 v12, v2
	s_nop 1
	v_permlane16_swap_b32_e32 v2, v12
	v_add_f32_e32 v2, v2, v12
	s_waitcnt lgkmcnt(0)
	v_mov_b32_e32 v12, v2
	s_nop 1
	v_permlane32_swap_b32_e32 v2, v12
	v_add_f32_e32 v2, v2, v12
	v_fmac_f32_e32 v4, 0xbb000000, v2
	v_fmac_f32_e32 v8, 0xbb000000, v2
	v_mul_f32_e32 v4, v4, v4
	v_fmac_f32_e32 v9, 0xbb000000, v2
	v_fmac_f32_e32 v4, v8, v8
	v_fmac_f32_e32 v5, 0xbb000000, v2
	v_fmac_f32_e32 v4, v9, v9
	v_fmac_f32_e32 v10, 0xbb000000, v2
	v_fmac_f32_e32 v4, v5, v5
	v_fmac_f32_e32 v6, 0xbb000000, v2
	v_fmac_f32_e32 v4, v10, v10
	v_fmac_f32_e32 v11, 0xbb000000, v2
	v_fmac_f32_e32 v4, v6, v6
	v_fmac_f32_e32 v4, v11, v11
	v_fmac_f32_e32 v7, 0xbb000000, v2
	v_fmac_f32_e32 v4, v7, v7
	s_waitcnt lgkmcnt(0)
	s_nop 1
	v_add_f32_dpp v4, v4, v4 quad_perm:[1,0,3,2] row_mask:0xf bank_mask:0xf bound_ctrl:1
	s_waitcnt lgkmcnt(0)
	s_nop 1
	v_add_f32_dpp v4, v4, v4 quad_perm:[2,3,0,1] row_mask:0xf bank_mask:0xf bound_ctrl:1
	s_waitcnt lgkmcnt(0)
	s_nop 1
	v_add_f32_dpp v4, v4, v4 row_half_mirror row_mask:0xf bank_mask:0xf bound_ctrl:1
	s_waitcnt lgkmcnt(0)
	s_nop 1
	v_add_f32_dpp v4, v4, v4 row_ror:8 row_mask:0xf bank_mask:0xf bound_ctrl:1
	s_waitcnt lgkmcnt(0)
	v_mov_b32_e32 v5, v4
	s_nop 1
	v_permlane16_swap_b32_e32 v4, v5
	v_add_f32_e32 v4, v4, v5
	ds_bpermute_b32 v5, v129, v4
	s_and_saveexec_b64 s[2:3], s[6:7]
	s_cbranch_execz .LBB0_154
	s_waitcnt lgkmcnt(0)
	v_add_f32_e32 v4, v4, v5
	v_fmamk_f32 v4, v4, 0x3b000000, v240
	s_mov_b32 s0, 0xf800000
	v_mul_f32_e32 v5, 0x4f800000, v4
	v_cmp_gt_f32_e32 vcc, s0, v4
	v_mul_f32_e32 v2, 0x3b000000, v2
	s_nop 0
	v_cndmask_b32_e32 v4, v4, v5, vcc
	v_sqrt_f32_e32 v5, v4
	s_nop 0
	v_add_u32_e32 v6, -1, v5
	v_fma_f32 v8, -v6, v5, v4
	v_add_u32_e32 v7, 1, v5
	v_cmp_ge_f32_e64 s[76:77], 0, v8
	s_nop 1
	v_cndmask_b32_e64 v6, v5, v6, s[76:77]
	v_fma_f32 v5, -v7, v5, v4
	v_cmp_lt_f32_e64 s[76:77], 0, v5
	s_nop 1
	v_cndmask_b32_e64 v5, v6, v7, s[76:77]
	v_mul_f32_e32 v6, 0x37800000, v5
	v_cndmask_b32_e32 v5, v5, v6, vcc
	v_cmp_class_f32_e32 vcc, v4, v239
	s_nop 1
	v_cndmask_b32_e32 v4, v5, v4, vcc
	v_div_scale_f32 v5, s[76:77], v4, v4, 1.0
	v_rcp_f32_e32 v6, v5
	s_nop 0
	v_fma_f32 v7, -v5, v6, 1.0
	v_fmac_f32_e32 v6, v7, v6
	v_div_scale_f32 v7, vcc, 1.0, v4, 1.0
	v_mul_f32_e32 v8, v7, v6
	v_fma_f32 v9, -v5, v8, v7
	v_fmac_f32_e32 v8, v9, v6
	v_fma_f32 v5, -v5, v8, v7
	v_div_fmas_f32 v5, v5, v6, v8
	v_div_fixup_f32 v4, v5, v4, 1.0
	v_mov_b32_e32 v5, s92
	ds_write2_b32 v5, v2, v4 offset0:6 offset1:7
	s_branch .LBB0_154
